# speedup vs baseline: 1.0048x; 1.0023x over previous
; __device__ __forceinline__ float bf2f(bh v) { return __uint_as_float(((unsigned)v) << 16); }
; __device__ __forceinline__ void merge_phase(const bh* __restrict__ ys, const bh* __restrict__ G, const bh* __restrict__ Wb,
;                             const float* __restrict__ ssp, bh* __restrict__ merged, char* lds) {
;     ...
;       __syncthreads();
;       {
;         int lrb = lr0; asm volatile("" : "+v"(lrb));
; #pragma unroll
;         for (int m = 0; m < 4; ++m)
; #pragma unroll
;           for (int j = 0; j < 4; ++j) {
;             const int lr = lrb + m * 16 + j;
;             const float sc = scs[lr];
; #pragma unroll
;             for (int q = 0; q < 4; ++q) accM[m][q][j] += accP[m][q][j] * sc * bf2f(gs[lr * 136 + lc0 + q * 16]);
;           }
;       }
;       __syncthreads();
.LBB0_793:
	s_or_b64 exec, exec, s[8:9]
	v_mov_b32_e32 v64, v91
	s_waitcnt lgkmcnt(0)
	s_barrier
	s_movk_i32 s8, 0x110
	v_lshl_add_u32 v65, v64, 2, 32
	v_add_u32_e32 v66, 0x11000, v65
	v_mad_u64_u32 v[64:65], s[8:9], v64, s8, v[90:91]
	s_add_i32 s20, s20, 1
	s_add_u32 s2, s2, 0x400
	s_addc_u32 s3, s3, 0
	s_add_u32 s4, s4, 0x100000
	s_addc_u32 s5, s5, 0
	s_cmp_eq_u32 s20, 4
	ds_read2_b32 v[244:245], v66 offset1:1
	ds_read_u16 v228, v64 offset:96
	ds_read_u16 v229, v64 offset:368
	ds_read_u16 v230, v64
	ds_read_u16 v231, v64 offset:272
	ds_read_u16 v232, v64 offset:32
	ds_read_u16 v233, v64 offset:304
	ds_read_u16 v234, v64 offset:64
	ds_read_u16 v235, v64 offset:336
	s_waitcnt lgkmcnt(0)
	v_pk_mul_f32 v[56:57], v[56:57], v[244:245]
	v_lshlrev_b32_e32 v228, 16, v228
	v_lshlrev_b32_e32 v229, 16, v229
	v_pk_fma_f32 v[160:161], v[56:57], v[228:229], v[160:161]
	v_pk_mul_f32 v[60:61], v[60:61], v[244:245]
	v_pk_mul_f32 v[52:53], v[52:53], v[244:245]
	v_pk_mul_f32 v[48:49], v[48:49], v[244:245]
	v_lshlrev_b32_e32 v230, 16, v230
	v_lshlrev_b32_e32 v231, 16, v231
	v_pk_fma_f32 v[182:183], v[60:61], v[230:231], v[182:183]
	v_lshlrev_b32_e32 v232, 16, v232
	v_lshlrev_b32_e32 v233, 16, v233
	v_pk_fma_f32 v[172:173], v[52:53], v[232:233], v[172:173]
	v_lshlrev_b32_e32 v234, 16, v234
	v_lshlrev_b32_e32 v235, 16, v235
	v_pk_fma_f32 v[168:169], v[48:49], v[234:235], v[168:169]
	ds_read2_b32 v[244:245], v66 offset0:2 offset1:3
	ds_read_u16 v228, v64 offset:640
	ds_read_u16 v229, v64 offset:912
	ds_read_u16 v230, v64 offset:544
	ds_read_u16 v231, v64 offset:816
	ds_read_u16 v232, v64 offset:576
	ds_read_u16 v233, v64 offset:848
	ds_read_u16 v234, v64 offset:608
	ds_read_u16 v235, v64 offset:880
	s_waitcnt lgkmcnt(0)
	v_pk_mul_f32 v[52:53], v[58:59], v[244:245]
	v_lshlrev_b32_e32 v228, 16, v228
	v_lshlrev_b32_e32 v229, 16, v229
	v_pk_fma_f32 v[156:157], v[52:53], v[228:229], v[156:157]
	v_pk_mul_f32 v[56:57], v[62:63], v[244:245]
	v_pk_mul_f32 v[54:55], v[54:55], v[244:245]
	v_pk_mul_f32 v[48:49], v[50:51], v[244:245]
	v_lshlrev_b32_e32 v230, 16, v230
	v_lshlrev_b32_e32 v231, 16, v231
	v_pk_fma_f32 v[174:175], v[56:57], v[230:231], v[174:175]
	v_lshlrev_b32_e32 v232, 16, v232
	v_lshlrev_b32_e32 v233, 16, v233
	v_pk_fma_f32 v[170:171], v[54:55], v[232:233], v[170:171]
	v_lshlrev_b32_e32 v234, 16, v234
	v_lshlrev_b32_e32 v235, 16, v235
	v_pk_fma_f32 v[166:167], v[48:49], v[234:235], v[166:167]
	ds_read2_b32 v[244:245], v66 offset0:16 offset1:17
	ds_read_u16 v228, v64 offset:4448
	ds_read_u16 v229, v64 offset:4720
	ds_read_u16 v230, v64 offset:4352
	ds_read_u16 v231, v64 offset:4624
	ds_read_u16 v232, v64 offset:4384
	ds_read_u16 v233, v64 offset:4656
	ds_read_u16 v234, v64 offset:4416
	ds_read_u16 v235, v64 offset:4688
	s_waitcnt lgkmcnt(0)
	v_pk_mul_f32 v[44:45], v[44:45], v[244:245]
	v_lshlrev_b32_e32 v228, 16, v228
	v_lshlrev_b32_e32 v229, 16, v229
	v_pk_fma_f32 v[128:129], v[44:45], v[228:229], v[128:129]
	v_pk_mul_f32 v[40:41], v[40:41], v[244:245]
	v_pk_mul_f32 v[36:37], v[36:37], v[244:245]
	v_pk_mul_f32 v[32:33], v[32:33], v[244:245]
	v_lshlrev_b32_e32 v230, 16, v230
	v_lshlrev_b32_e32 v231, 16, v231
	v_pk_fma_f32 v[146:147], v[40:41], v[230:231], v[146:147]
	v_lshlrev_b32_e32 v232, 16, v232
	v_lshlrev_b32_e32 v233, 16, v233
	v_pk_fma_f32 v[136:137], v[36:37], v[232:233], v[136:137]
	v_lshlrev_b32_e32 v234, 16, v234
	v_lshlrev_b32_e32 v235, 16, v235
	v_pk_fma_f32 v[132:133], v[32:33], v[234:235], v[132:133]
	ds_read2_b32 v[244:245], v66 offset0:18 offset1:19
	ds_read_u16 v228, v64 offset:4992
	ds_read_u16 v229, v64 offset:5264
	ds_read_u16 v230, v64 offset:4896
	ds_read_u16 v231, v64 offset:5168
	ds_read_u16 v232, v64 offset:4928
	ds_read_u16 v233, v64 offset:5200
	ds_read_u16 v234, v64 offset:4960
	ds_read_u16 v235, v64 offset:5232
	s_waitcnt lgkmcnt(0)
	v_pk_mul_f32 v[36:37], v[46:47], v[244:245]
	v_lshlrev_b32_e32 v228, 16, v228
	v_lshlrev_b32_e32 v229, 16, v229
	v_pk_fma_f32 v[126:127], v[36:37], v[228:229], v[126:127]
	v_pk_mul_f32 v[40:41], v[42:43], v[244:245]
	v_pk_mul_f32 v[38:39], v[38:39], v[244:245]
	v_pk_mul_f32 v[32:33], v[34:35], v[244:245]
	v_lshlrev_b32_e32 v230, 16, v230
	v_lshlrev_b32_e32 v231, 16, v231
	v_pk_fma_f32 v[140:141], v[40:41], v[230:231], v[140:141]
	v_lshlrev_b32_e32 v232, 16, v232
	v_lshlrev_b32_e32 v233, 16, v233
	v_pk_fma_f32 v[134:135], v[38:39], v[232:233], v[134:135]
	v_lshlrev_b32_e32 v234, 16, v234
	v_lshlrev_b32_e32 v235, 16, v235
	v_pk_fma_f32 v[130:131], v[32:33], v[234:235], v[130:131]
	ds_read2_b32 v[244:245], v66 offset0:32 offset1:33
	ds_read_u16 v228, v64 offset:8800
	ds_read_u16 v229, v64 offset:9072
	ds_read_u16 v230, v64 offset:8704
	ds_read_u16 v231, v64 offset:8976
	ds_read_u16 v232, v64 offset:8736
	ds_read_u16 v233, v64 offset:9008
	ds_read_u16 v234, v64 offset:8768
	ds_read_u16 v235, v64 offset:9040
	s_waitcnt lgkmcnt(0)
; __device__ __forceinline__ float bf2f(bh v) { return __uint_as_float(((unsigned)v) << 16); }
; __device__ __forceinline__ void merge_phase(const bh* __restrict__ ys, const bh* __restrict__ G, const bh* __restrict__ Wb,
;                             const float* __restrict__ ssp, bh* __restrict__ merged, char* lds) {
;     ...
;       __syncthreads();
;       {
;         int lrb = lr0; asm volatile("" : "+v"(lrb));
; #pragma unroll
;         for (int m = 0; m < 4; ++m)
; #pragma unroll
;           for (int j = 0; j < 4; ++j) {
;             const int lr = lrb + m * 16 + j;
;             const float sc = scs[lr];
; #pragma unroll
;             for (int q = 0; q < 4; ++q) accM[m][q][j] += accP[m][q][j] * sc * bf2f(gs[lr * 136 + lc0 + q * 16]);
;           }
;       }
;       __syncthreads();
	v_pk_mul_f32 v[24:25], v[24:25], v[244:245]
	v_lshlrev_b32_e32 v228, 16, v228
	v_lshlrev_b32_e32 v229, 16, v229
	v_pk_fma_f32 v[112:113], v[24:25], v[228:229], v[112:113]
	v_pk_mul_f32 v[28:29], v[28:29], v[244:245]
	v_pk_mul_f32 v[20:21], v[20:21], v[244:245]
	v_pk_mul_f32 v[16:17], v[16:17], v[244:245]
	v_lshlrev_b32_e32 v230, 16, v230
	v_lshlrev_b32_e32 v231, 16, v231
	v_pk_fma_f32 v[124:125], v[28:29], v[230:231], v[124:125]
	v_lshlrev_b32_e32 v232, 16, v232
	v_lshlrev_b32_e32 v233, 16, v233
	v_pk_fma_f32 v[120:121], v[20:21], v[232:233], v[120:121]
	v_lshlrev_b32_e32 v234, 16, v234
	v_lshlrev_b32_e32 v235, 16, v235
	v_pk_fma_f32 v[116:117], v[16:17], v[234:235], v[116:117]
	ds_read2_b32 v[244:245], v66 offset0:34 offset1:35
	ds_read_u16 v228, v64 offset:9344
	ds_read_u16 v229, v64 offset:9616
	ds_read_u16 v230, v64 offset:9248
	ds_read_u16 v231, v64 offset:9520
	ds_read_u16 v232, v64 offset:9280
	ds_read_u16 v233, v64 offset:9552
	ds_read_u16 v234, v64 offset:9312
	ds_read_u16 v235, v64 offset:9584
	s_waitcnt lgkmcnt(0)
	v_pk_mul_f32 v[20:21], v[26:27], v[244:245]
	v_lshlrev_b32_e32 v228, 16, v228
	v_lshlrev_b32_e32 v229, 16, v229
	v_pk_fma_f32 v[110:111], v[20:21], v[228:229], v[110:111]
	v_pk_mul_f32 v[24:25], v[30:31], v[244:245]
	v_pk_mul_f32 v[22:23], v[22:23], v[244:245]
	v_pk_mul_f32 v[16:17], v[18:19], v[244:245]
	v_lshlrev_b32_e32 v230, 16, v230
	v_lshlrev_b32_e32 v231, 16, v231
	v_pk_fma_f32 v[122:123], v[24:25], v[230:231], v[122:123]
	v_lshlrev_b32_e32 v232, 16, v232
	v_lshlrev_b32_e32 v233, 16, v233
	v_pk_fma_f32 v[118:119], v[22:23], v[232:233], v[118:119]
	v_lshlrev_b32_e32 v234, 16, v234
	v_lshlrev_b32_e32 v235, 16, v235
	v_pk_fma_f32 v[114:115], v[16:17], v[234:235], v[114:115]
	ds_read2_b32 v[244:245], v66 offset0:48 offset1:49
	ds_read_u16 v228, v64 offset:13152
	ds_read_u16 v229, v64 offset:13424
	ds_read_u16 v230, v64 offset:13056
	ds_read_u16 v231, v64 offset:13328
	ds_read_u16 v232, v64 offset:13088
	ds_read_u16 v233, v64 offset:13360
	ds_read_u16 v234, v64 offset:13120
	ds_read_u16 v235, v64 offset:13392
	s_waitcnt lgkmcnt(0)
	v_pk_mul_f32 v[12:13], v[12:13], v[244:245]
	v_lshlrev_b32_e32 v228, 16, v228
	v_lshlrev_b32_e32 v229, 16, v229
	v_pk_fma_f32 v[96:97], v[12:13], v[228:229], v[96:97]
	v_pk_mul_f32 v[8:9], v[8:9], v[244:245]
	v_pk_mul_f32 v[4:5], v[4:5], v[244:245]
	v_pk_mul_f32 v[0:1], v[0:1], v[244:245]
	v_lshlrev_b32_e32 v230, 16, v230
	v_lshlrev_b32_e32 v231, 16, v231
	v_pk_fma_f32 v[108:109], v[8:9], v[230:231], v[108:109]
	v_lshlrev_b32_e32 v232, 16, v232
	v_lshlrev_b32_e32 v233, 16, v233
	v_pk_fma_f32 v[104:105], v[4:5], v[232:233], v[104:105]
	v_lshlrev_b32_e32 v234, 16, v234
	v_lshlrev_b32_e32 v235, 16, v235
	v_pk_fma_f32 v[100:101], v[0:1], v[234:235], v[100:101]
	ds_read2_b32 v[244:245], v66 offset0:50 offset1:51
	ds_read_u16 v228, v64 offset:13696
	ds_read_u16 v229, v64 offset:13968
	ds_read_u16 v230, v64 offset:13600
	ds_read_u16 v231, v64 offset:13872
	ds_read_u16 v232, v64 offset:13632
	ds_read_u16 v233, v64 offset:13904
	ds_read_u16 v234, v64 offset:13664
	ds_read_u16 v235, v64 offset:13936
	s_waitcnt lgkmcnt(0)
	s_barrier
	v_pk_mul_f32 v[4:5], v[14:15], v[244:245]
	v_lshlrev_b32_e32 v228, 16, v228
	v_lshlrev_b32_e32 v229, 16, v229
	v_pk_fma_f32 v[94:95], v[4:5], v[228:229], v[94:95]
	v_pk_mul_f32 v[8:9], v[10:11], v[244:245]
	v_pk_mul_f32 v[6:7], v[6:7], v[244:245]
	v_pk_mul_f32 v[0:1], v[2:3], v[244:245]
	v_lshlrev_b32_e32 v230, 16, v230
	v_lshlrev_b32_e32 v231, 16, v231
	v_pk_fma_f32 v[106:107], v[8:9], v[230:231], v[106:107]
	v_lshlrev_b32_e32 v232, 16, v232
	v_lshlrev_b32_e32 v233, 16, v233
	v_pk_fma_f32 v[102:103], v[6:7], v[232:233], v[102:103]
	v_lshlrev_b32_e32 v234, 16, v234
	v_lshlrev_b32_e32 v235, 16, v235
	v_pk_fma_f32 v[98:99], v[0:1], v[234:235], v[98:99]
	s_cbranch_scc1 .LBB0_790
